# RG-LRU chunk loop: conv tap/bias loads issued before stage 5 of the previous chunk (one blanket wait at the chunk top) instead of at the chunk top with progressive waits
# speedup vs baseline: 1.0022x; 1.0022x over previous
; __device__ __forceinline__ void rglru_item(const Ptrs& P, unsigned char* lds, int b, int n, int tid) {
;     const int lane = tid & 63, w = __builtin_amdgcn_readfirstlane(tid >> 6), g = lane >> 4, r16 = lane & 15;
;     bf16_t* XCb = (bf16_t*)lds;
;     float* XCf = (float*)(lds + 17408);
;     float* LA = (float*)(lds + 17408 + 32768);
;     float* LB = LA + 8192;
;     const size_t rowb = (size_t)b * T;
;     const int ce = 16 * w + r16, ch = n * 128 + ce;
;     bf16x8 Ba[4], Bx[4];
; #pragma unroll
;     for (int ks = 0; ks < 4; ++ks) { Ba[ks] = *(const bf16x8*)(P.WgaT + (size_t)ch * 128 + 32 * ks + 8 * g); Bx[ks] = *(const bf16x8*)(P.WgxT + (size_t)ch * 128 + 32 * ks + 8 * g); }
;     const float ba = P.bga[ch], bx = P.bgx[ch];
;     const float sp8 = 8.f * log1pf(expf(-P.lam[ch]));
.LBB0_450:
	s_cmp_lt_i32 s58, 3
	s_cselect_b64 s[4:5], -1, 0
	s_and_b64 s[40:41], s[4:5], s[0:1]
	s_andn2_b64 vcc, exec, s[40:41]
	s_cbranch_vccnz .LBB0_933
	s_cmp_gt_u32 s2, 63
	v_bfe_u32 v90, v188, 4, 2
	s_cbranch_scc1 .LBB0_460
	v_readfirstlane_b32 s0, v188
	s_lshr_b32 s0, s0, 2
	v_and_b32_e32 v66, 15, v188
	s_and_b32 s0, s0, 0x3ffffff0
	v_or_b32_e32 v67, s0, v66
	s_lshl_b32 s0, s2, 7
	s_and_b32 s1, s0, 0x780
	v_add_u32_e32 v72, s1, v67
	v_mov_b32_e32 v73, 0
	v_lshlrev_b64 v[0:1], 2, v[72:73]
	v_lshl_add_u64 v[2:3], s[22:23], 0, v[0:1]
	global_load_dword v32, v[2:3], off
	s_mov_b32 s5, 0xbfb8aa3b
	s_mov_b32 s7, 0x42ce8ed0
	s_mov_b32 s8, 0xc2b17218
	v_lshlrev_b64 v[2:3], 8, v[72:73]
	v_lshlrev_b32_e32 v64, 4, v90
	v_mov_b32_e32 v68, 0x7f800000
	v_mov_b32_e32 v65, v73
	v_lshl_add_u64 v[4:5], s[64:65], 0, v[2:3]
	v_lshl_add_u64 v[2:3], s[70:71], 0, v[2:3]
	v_lshl_add_u64 v[20:21], v[4:5], 0, v[64:65]
	v_lshl_add_u64 v[28:29], v[2:3], 0, v[64:65]
	s_mov_b32 s9, 0x3f2aaaab
	s_mov_b32 s10, 0x3f317218
	v_mov_b32_e32 v34, 0x3ecc95a3
	s_lshl_b32 s4, s2, 9
	v_lshl_add_u64 v[6:7], s[16:17], 0, v[0:1]
	v_lshl_add_u64 v[0:1], s[20:21], 0, v[0:1]
	v_lshrrev_b32_e32 v93, 3, v188
	s_and_b32 s6, s4, 0x6000
	global_load_dword v91, v[6:7], off
	global_load_dword v92, v[0:1], off
	s_nop 0
	global_load_dwordx4 v[0:3], v[20:21], off
	global_load_dwordx4 v[4:7], v[20:21], off offset:64
	global_load_dwordx4 v[8:11], v[28:29], off
	global_load_dwordx4 v[12:15], v[28:29], off offset:64
	v_sub_u32_e64 v48, v93, 1 clamp
	v_or_b32_e32 v48, s6, v48
	v_or_b32_e32 v94, s6, v93
	v_lshlrev_b32_e32 v48, 12, v48
	v_mov_b32_e32 v49, v73
	v_lshlrev_b32_e32 v56, 12, v94
	v_mov_b32_e32 v57, v73
	s_mov_b32 s0, 0x7f800000
	v_add_u32_e32 v88, 0, v64
	v_lshlrev_b32_e32 v64, 9, v90
	v_add_lshl_u32 v64, v67, v64, 2
	s_add_i32 s4, 0, 0xc400
	v_add_u32_e32 v97, 0, v64
	v_mul_u32_u24_e32 v66, 0x110, v66
	s_mov_b32 s3, 0
	v_lshl_add_u32 v122, v188, 2, s4
	v_add_u32_e32 v124, v88, v66
	v_mov_b32_e32 v125, 0x260
	v_mov_b32_e32 v127, 0
	s_waitcnt vmcnt(0)
	v_mul_f32_e32 v16, 0xbfb8aa3b, v32
	v_fma_f32 v17, v32, s5, -v16
	v_rndne_f32_e32 v18, v16
	v_fmamk_f32 v17, v32, 0xb2a5705f, v17
	v_sub_f32_e32 v16, v16, v18
	v_add_f32_e32 v16, v16, v17
	v_cvt_i32_f32_e32 v33, v18
	v_exp_f32_e32 v35, v16
	v_cmp_nlt_f32_e32 vcc, s7, v32
	global_load_dwordx4 v[16:19], v[20:21], off offset:128
	s_nop 0
	global_load_dwordx4 v[20:23], v[20:21], off offset:192
	s_nop 0
	global_load_dwordx4 v[24:27], v[28:29], off offset:128
	s_nop 0
	global_load_dwordx4 v[28:31], v[28:29], off offset:192
	s_or_b32 s7, s6, 1
	v_ldexp_f32 v33, v35, v33
	v_cndmask_b32_e32 v33, 0, v33, vcc
	v_cmp_ngt_f32_e32 vcc, s8, v32
	s_or_b32 s8, s6, 2
	s_nop 0
	v_cndmask_b32_e32 v65, v68, v33, vcc
	v_add_f32_e32 v35, 1.0, v65
	v_add_f32_e32 v36, -1.0, v35
	v_frexp_mant_f32_e32 v37, v35
	v_cvt_f64_f32_e32 v[32:33], v35
	v_sub_f32_e32 v38, v36, v35
	v_frexp_exp_i32_f64_e32 v32, v[32:33]
	v_cmp_gt_f32_e32 vcc, s9, v37
	v_sub_f32_e32 v36, v65, v36
	v_add_f32_e32 v33, 1.0, v38
	v_subbrev_co_u32_e32 v32, vcc, 0, v32, vcc
	v_add_f32_e32 v33, v36, v33
	v_sub_u32_e32 v36, 0, v32
	v_cvt_f32_i32_e32 v32, v32
	v_ldexp_f32 v35, v35, v36
	v_ldexp_f32 v33, v33, v36
	v_add_f32_e32 v36, -1.0, v35
	v_add_f32_e32 v37, 1.0, v35
	v_add_f32_e32 v38, 1.0, v36
	v_add_f32_e32 v39, -1.0, v37
	v_sub_f32_e32 v38, v35, v38
	v_sub_f32_e32 v35, v35, v39
	v_mul_f32_e32 v39, 0x3f317218, v32
	v_add_f32_e32 v38, v33, v38
	v_add_f32_e32 v33, v33, v35
	v_fma_f32 v35, v32, s10, -v39
	v_add_f32_e32 v40, v36, v38
	v_add_f32_e32 v41, v37, v33
	v_fmamk_f32 v32, v32, 0xb102e308, v35
	v_sub_f32_e32 v35, v36, v40
	v_sub_f32_e32 v36, v37, v41
	v_rcp_f32_e32 v37, v41
	v_add_f32_e32 v42, v39, v32
	v_add_f32_e32 v33, v33, v36
	v_sub_f32_e32 v36, v42, v39
	v_sub_f32_e32 v32, v32, v36
	v_mul_f32_e32 v36, v40, v37
	v_add_f32_e32 v35, v38, v35
	v_mul_f32_e32 v38, v41, v36
	v_fma_f32 v39, v36, v41, -v38
	v_fmac_f32_e32 v39, v36, v33
	v_add_f32_e32 v43, v38, v39
	v_sub_f32_e32 v44, v40, v43
	v_sub_f32_e32 v38, v43, v38
	v_sub_f32_e32 v40, v40, v44
	v_sub_f32_e32 v38, v38, v39
	v_sub_f32_e32 v39, v40, v43
	v_add_f32_e32 v35, v35, v39
	v_add_f32_e32 v35, v38, v35
	v_add_f32_e32 v38, v44, v35
	v_mul_f32_e32 v39, v37, v38
	v_sub_f32_e32 v40, v44, v38
	v_mul_f32_e32 v43, v41, v39
	v_add_f32_e32 v35, v35, v40
	v_add_f32_e32 v40, v36, v39
	v_fma_f32 v41, v39, v41, -v43
	v_sub_f32_e32 v36, v40, v36
	v_fmac_f32_e32 v41, v39, v33
	v_sub_f32_e32 v33, v39, v36
	v_add_f32_e32 v36, v43, v41
	v_sub_f32_e32 v39, v36, v43
	v_sub_f32_e32 v43, v38, v36
	v_sub_f32_e32 v38, v38, v43
	v_sub_f32_e32 v36, v38, v36
	v_sub_f32_e32 v39, v39, v41
	v_add_f32_e32 v35, v35, v36
	v_add_f32_e32 v35, v39, v35
	v_add_f32_e32 v35, v43, v35
	v_mul_f32_e32 v35, v37, v35
	v_add_f32_e32 v33, v33, v35
	v_add_f32_e32 v35, v40, v33
	v_mul_f32_e32 v36, v35, v35
	v_fmac_f32_e32 v34, 0x3e9b6dac, v36
	v_sub_f32_e32 v37, v35, v40
	v_ldexp_f32 v38, v35, 1
	v_mul_f32_e32 v35, v35, v36
	v_fmaak_f32 v34, v36, v34, 0x3f2aaada
	v_mul_f32_e32 v34, v35, v34
	v_add_f32_e32 v35, v38, v34
	v_sub_f32_e32 v33, v33, v37
	v_sub_f32_e32 v36, v35, v38
	v_ldexp_f32 v33, v33, 1
	v_sub_f32_e32 v34, v34, v36
	v_add_f32_e32 v33, v33, v34
	v_add_f32_e32 v34, v35, v33
	v_sub_f32_e32 v35, v34, v35
	v_add_f32_e32 v36, v42, v34
	v_sub_f32_e32 v33, v33, v35
	v_sub_f32_e32 v35, v36, v42
	v_sub_f32_e32 v37, v36, v35
	v_sub_f32_e32 v34, v34, v35
	v_add_f32_e32 v35, v32, v33
	v_sub_f32_e32 v37, v42, v37
	v_sub_f32_e32 v38, v35, v32
	v_add_f32_e32 v34, v34, v37
	v_sub_f32_e32 v37, v35, v38
	v_sub_f32_e32 v33, v33, v38
	v_sub_f32_e32 v32, v32, v37
	v_add_f32_e32 v69, v33, v32
; #define RG_LOAD(T0) do { _Pragma("unroll") for (int k = 0; k < 4; ++k) { int tk = (T0) + tt - 3 + k; tk = tk < 0 ? 0 : tk; const bf16_t* xp = P.XR + (rowb + tk) * 2048 + cg0; \
;             xr[k][0] = *(const u32x4*)xp; xr[k][1] = *(const u32x4*)(xp + 8); } } while (0)
; __device__ __forceinline__ void rglru_item(const Ptrs& P, unsigned char* lds, int b, int n, int tid) {
;     ...
;     const size_t rowb = (size_t)b * T;
;     const int ce = 16 * w + r16, ch = n * 128 + ce;
;     bf16x8 Ba[4], Bx[4];
; #pragma unroll
;     for (int ks = 0; ks < 4; ++ks) { Ba[ks] = *(const bf16x8*)(P.WgaT + (size_t)ch * 128 + 32 * ks + 8 * g); Bx[ks] = *(const bf16x8*)(P.WgxT + (size_t)ch * 128 + 32 * ks + 8 * g); }
;     const float ba = P.bga[ch], bx = P.bgx[ch];
;     const float sp8 = 8.f * log1pf(expf(-P.lam[ch]));
;     const bool big = __any(sp8 > 0.14f);
;     float h = 0.f;
;     const int tt = tid >> 3, c0 = (tid & 7) * 16, cg0 = n * 128 + c0;
;     u32x4 xr[4][2];
;     ...
;     RG_LOAD(0);
;     ...
;             for (int e = 0; e < 16; e += 4) { const f32x4 v = *(const f32x4*)(P.conv_b + cg0 + e); xc[e] = v[0]; xc[e + 1] = v[1]; xc[e + 2] = v[2]; xc[e + 3] = v[3]; }
; #pragma unroll
;             for (int k = 0; k < 4; ++k) { const float m = (t0 + tt - 3 + k) >= 0 ? 1.f : 0.f;
;                 float cwk[16];
; #pragma unroll
;                 for (int e = 0; e < 16; e += 4) { const f32x4 c = *(const f32x4*)(P.conv_w + k * 2048 + cg0 + e); cwk[e] = c[0]; cwk[e + 1] = c[1]; cwk[e + 2] = c[2]; cwk[e + 3] = c[3]; }
	v_add_f32_e32 v32, v35, v34
	v_add_f32_e32 v70, v36, v32
	v_sub_f32_e32 v33, v70, v36
	v_sub_f32_e32 v71, v32, v33
	v_lshlrev_b32_e32 v32, 4, v188
	v_and_b32_e32 v76, 0x70, v32
	v_or_b32_e32 v77, s1, v76
	v_sub_u32_e64 v32, v93, 3 clamp
	v_sub_u32_e64 v40, v93, 2 clamp
	v_lshlrev_b32_e32 v72, 1, v77
	v_or_b32_e32 v32, s6, v32
	v_or_b32_e32 v40, s6, v40
	v_lshl_add_u64 v[74:75], s[24:25], 0, v[72:73]
	v_lshlrev_b32_e32 v32, 12, v32
	v_mov_b32_e32 v33, v73
	v_lshlrev_b32_e32 v40, 12, v40
	v_mov_b32_e32 v41, v73
	v_lshl_add_u64 v[36:37], v[74:75], 0, v[32:33]
	v_lshl_add_u64 v[44:45], v[74:75], 0, v[40:41]
	v_lshl_add_u64 v[52:53], v[74:75], 0, v[48:49]
	v_lshl_add_u64 v[60:61], v[74:75], 0, v[56:57]
	global_load_dwordx4 v[32:35], v[36:37], off offset:16
	s_nop 0
	global_load_dwordx4 v[36:39], v[36:37], off
	s_nop 0
	global_load_dwordx4 v[40:43], v[44:45], off offset:16
	s_nop 0
	global_load_dwordx4 v[44:47], v[44:45], off
	s_nop 0
	global_load_dwordx4 v[48:51], v[52:53], off offset:16
	s_nop 0
	global_load_dwordx4 v[52:55], v[52:53], off
	s_nop 0
	global_load_dwordx4 v[56:59], v[60:61], off offset:16
	s_nop 0
	global_load_dwordx4 v[60:63], v[60:61], off
	v_add_f32_e32 v69, v69, v71
	s_mov_b32 s1, 0x33800000
	v_add_f32_e32 v69, v70, v69
	v_cmp_neq_f32_e32 vcc, s0, v65
	s_add_i32 s0, 0, 0x14400
	v_add_u32_e32 v98, s0, v64
	v_cndmask_b32_e32 v68, v68, v69, vcc
	v_cmp_lt_f32_e64 vcc, |v65|, s1
	v_lshlrev_b32_e32 v69, 2, v76
	s_movk_i32 s1, 0x80
	v_cndmask_b32_e32 v65, v68, v65, vcc
	v_mul_f32_e32 v96, 0xc1000000, v65
	v_add_u32_e32 v65, 0x4000, v64
	v_add_u32_e32 v106, s4, v65
	v_add_u32_e32 v107, s0, v65
	v_add_u32_e32 v65, 0x4200, v64
	v_add_u32_e32 v108, s4, v65
	v_add_u32_e32 v109, s0, v65
	v_add_u32_e32 v65, 0x4400, v64
	v_add_u32_e32 v110, s4, v65
	v_add_u32_e32 v111, s0, v65
	v_add_u32_e32 v65, 0x4600, v64
	v_add_u32_e32 v112, s4, v65
	v_add_u32_e32 v113, s0, v65
	v_add_u32_e32 v65, 0x6000, v64
	v_add_u32_e32 v114, s4, v65
	v_add_u32_e32 v115, s0, v65
	v_add_u32_e32 v65, 0x6200, v64
	v_add_u32_e32 v116, s4, v65
	v_add_u32_e32 v117, s0, v65
	v_add_u32_e32 v65, 0x6400, v64
	v_add_u32_e32 v64, 0x6600, v64
	v_lshlrev_b32_e32 v68, 9, v93
	v_add_u32_e32 v118, s4, v65
	v_add_u32_e32 v119, s0, v65
	v_add_u32_e32 v120, s4, v64
	v_add_u32_e32 v121, s0, v64
	v_lshlrev_b32_e32 v64, 2, v77
	v_mov_b32_e32 v65, v73
	v_add3_u32 v95, 0, v68, v69
	v_add_u32_e32 v69, s0, v69
	v_cmp_gt_u32_e32 vcc, s1, v188
	v_lshl_add_u64 v[78:79], s[46:47], 0, v[64:65]
	s_mov_b64 s[0:1], 0x2000
	v_lshl_add_u64 v[80:81], v[78:79], 0, s[0:1]
	s_mov_b64 s[0:1], 0x4000
	v_lshl_add_u32 v70, v76, 1, 0
	v_mul_u32_u24_e32 v71, 0x110, v93
	v_lshl_add_u64 v[82:83], v[78:79], 0, s[0:1]
	s_mov_b64 s[0:1], 0x6000
	v_add_u32_e32 v99, 0x200, v98
	v_add_u32_e32 v100, 0x400, v98
	v_add_u32_e32 v101, 0x600, v98
	v_add_u32_e32 v102, 0x2000, v98
	v_add_u32_e32 v103, 0x2200, v98
	v_add_u32_e32 v104, 0x2400, v98
	v_add_u32_e32 v105, 0x2600, v98
	v_lshl_add_u64 v[76:77], s[48:49], 0, v[64:65]
	v_lshl_add_u64 v[84:85], v[78:79], 0, s[0:1]
	v_lshl_add_u64 v[86:87], s[26:27], 0, v[72:73]
	s_or_b32 s9, s6, 3
	v_add_u32_e32 v123, v70, v71
	s_mov_b32 s10, 0xf800000
	v_add_u32_e32 v126, v69, v68
	global_load_dwordx4 v[130:133], v[78:79], off
	global_load_dwordx4 v[134:137], v[80:81], off
	global_load_dwordx4 v[138:141], v[82:83], off
	global_load_dwordx4 v[142:145], v[78:79], off offset:16
	global_load_dwordx4 v[146:149], v[80:81], off offset:16
	global_load_dwordx4 v[150:153], v[82:83], off offset:16
	global_load_dwordx4 v[154:157], v[76:77], off
	global_load_dwordx4 v[158:161], v[76:77], off offset:16
	global_load_dwordx4 v[162:165], v[84:85], off
	global_load_dwordx4 v[166:169], v[84:85], off offset:16
	global_load_dwordx4 v[170:173], v[78:79], off offset:32
	global_load_dwordx4 v[174:177], v[76:77], off offset:32
	global_load_dwordx4 v[178:181], v[76:77], off offset:48
	global_load_dwordx4 v[182:185], v[78:79], off offset:48
	global_load_dwordx4 v[190:193], v[80:81], off offset:32
	global_load_dwordx4 v[194:197], v[80:81], off offset:48
	global_load_dwordx4 v[198:201], v[82:83], off offset:32
	global_load_dwordx4 v[202:205], v[84:85], off offset:32
	s_branch .LBB0_454
	s_nop 0
	s_nop 0
	s_nop 0
	s_nop 0
	s_nop 0
	s_nop 0
	s_nop 0
	s_nop 0
	s_nop 0
; __device__ __forceinline__ unsigned cvt_pk_bf16(float lo, float hi) { unsigned r; asm volatile("v_cvt_pk_bf16_f32 %0, %1, %2" : "=v"(r) : "v"(lo), "v"(hi)); return r; }
; __device__ __forceinline__ void rglru_item(const Ptrs& P, unsigned char* lds, int b, int n, int tid) {
;     ...
;     for (int chunk = 0; chunk < T / 64; ++chunk) {
;         const int t0 = chunk * 64;
;         u32x4 gc0, gc1;
;         {
;             float xc[16];
; #pragma unroll
;             for (int e = 0; e < 16; e += 4) { const f32x4 v = *(const f32x4*)(P.conv_b + cg0 + e); xc[e] = v[0]; xc[e + 1] = v[1]; xc[e + 2] = v[2]; xc[e + 3] = v[3]; }
; #pragma unroll
;             for (int k = 0; k < 4; ++k) { const float m = (t0 + tt - 3 + k) >= 0 ? 1.f : 0.f;
;                 float cwk[16];
; #pragma unroll
;                 for (int e = 0; e < 16; e += 4) { const f32x4 c = *(const f32x4*)(P.conv_w + k * 2048 + cg0 + e); cwk[e] = c[0]; cwk[e + 1] = c[1]; cwk[e + 2] = c[2]; cwk[e + 3] = c[3]; }
;                 const u32x4 xa = xr[k][0], xb2 = xr[k][1];
;                 const float xv[16] = {bflo(xa.x), bfhi(xa.x), bflo(xa.y), bfhi(xa.y), bflo(xa.z), bfhi(xa.z), bflo(xa.w), bfhi(xa.w),
;                                       bflo(xb2.x), bfhi(xb2.x), bflo(xb2.y), bfhi(xb2.y), bflo(xb2.z), bfhi(xb2.z), bflo(xb2.w), bfhi(xb2.w)};
; #pragma unroll
;                 for (int e = 0; e < 16; ++e) xc[e] += (cwk[e] * m) * xv[e]; }
;     ...
;         {
;             bf16_t* gp = P.RG + (rowb + t0 + tt) * 2048 + cg0;
;             const float* hp = LB + tt * 128 + c0;
;             u32x4 o0, o1;
;             o0.x = cvt_pk_bf16(hp[0] * bflo(gc0.x), hp[1] * bfhi(gc0.x)); o0.y = cvt_pk_bf16(hp[2] * bflo(gc0.y), hp[3] * bfhi(gc0.y));
;             o0.z = cvt_pk_bf16(hp[4] * bflo(gc0.z), hp[5] * bfhi(gc0.z)); o0.w = cvt_pk_bf16(hp[6] * bflo(gc0.w), hp[7] * bfhi(gc0.w));
;             o1.x = cvt_pk_bf16(hp[8] * bflo(gc1.x), hp[9] * bfhi(gc1.x)); o1.y = cvt_pk_bf16(hp[10] * bflo(gc1.y), hp[11] * bfhi(gc1.y));
;             o1.z = cvt_pk_bf16(hp[12] * bflo(gc1.z), hp[13] * bfhi(gc1.z)); o1.w = cvt_pk_bf16(hp[14] * bflo(gc1.w), hp[15] * bfhi(gc1.w));
;             *(u32x4*)gp = o0; *(u32x4*)(gp + 8) = o1;
;         }
.LBB0_453:
	s_or_b64 exec, exec, s[0:1]
	global_load_dwordx4 v[130:133], v[78:79], off
	global_load_dwordx4 v[134:137], v[80:81], off
	global_load_dwordx4 v[138:141], v[82:83], off
	global_load_dwordx4 v[142:145], v[78:79], off offset:16
	global_load_dwordx4 v[146:149], v[80:81], off offset:16
	global_load_dwordx4 v[150:153], v[82:83], off offset:16
	global_load_dwordx4 v[154:157], v[76:77], off
	global_load_dwordx4 v[158:161], v[76:77], off offset:16
	global_load_dwordx4 v[162:165], v[84:85], off
	global_load_dwordx4 v[166:169], v[84:85], off offset:16
	global_load_dwordx4 v[170:173], v[78:79], off offset:32
	global_load_dwordx4 v[174:177], v[76:77], off offset:32
	global_load_dwordx4 v[178:181], v[76:77], off offset:48
	global_load_dwordx4 v[182:185], v[78:79], off offset:48
	global_load_dwordx4 v[190:193], v[80:81], off offset:32
	global_load_dwordx4 v[194:197], v[80:81], off offset:48
	global_load_dwordx4 v[198:201], v[82:83], off offset:32
	global_load_dwordx4 v[202:205], v[84:85], off offset:32
	s_waitcnt lgkmcnt(0)
	s_barrier
	ds_read_b64 v[128:129], v126
	s_waitcnt vmcnt(18)
	v_lshlrev_b32_e32 v72, 16, v68
	v_and_b32_e32 v68, 0xffff0000, v68
	s_add_i32 s3, s3, 1
	s_cmpk_lg_i32 s3, 0x80
	s_waitcnt lgkmcnt(0)
	v_mul_f32_e32 v68, v129, v68
	v_mul_f32_e32 v72, v128, v72
	v_cvt_pk_bf16_f32 v68, v72, v68
	ds_read_b64 v[128:129], v126 offset:8
	v_lshlrev_b32_e32 v72, 16, v69
	v_and_b32_e32 v69, 0xffff0000, v69
	s_waitcnt lgkmcnt(0)
	v_mul_f32_e32 v69, v129, v69
	v_mul_f32_e32 v72, v128, v72
	v_cvt_pk_bf16_f32 v69, v72, v69
	ds_read_b64 v[128:129], v126 offset:16
	v_lshlrev_b32_e32 v72, 16, v70
	v_and_b32_e32 v70, 0xffff0000, v70
	s_waitcnt lgkmcnt(0)
	v_mul_f32_e32 v70, v129, v70
	v_mul_f32_e32 v72, v128, v72
	v_cvt_pk_bf16_f32 v70, v72, v70
	ds_read_b64 v[128:129], v126 offset:24
	v_lshlrev_b32_e32 v72, 16, v71
	v_and_b32_e32 v71, 0xffff0000, v71
	s_waitcnt lgkmcnt(0)
	v_mul_f32_e32 v71, v129, v71
	v_mul_f32_e32 v72, v128, v72
	v_cvt_pk_bf16_f32 v71, v72, v71
	ds_read_b64 v[128:129], v126 offset:32
	v_lshlrev_b32_e32 v72, 16, v64
	v_and_b32_e32 v64, 0xffff0000, v64
	s_waitcnt lgkmcnt(0)
	v_mul_f32_e32 v64, v129, v64
	v_mul_f32_e32 v72, v128, v72
	v_cvt_pk_bf16_f32 v64, v72, v64
	ds_read_b64 v[128:129], v126 offset:40
	v_lshlrev_b32_e32 v72, 16, v65
	v_and_b32_e32 v65, 0xffff0000, v65
	s_waitcnt lgkmcnt(0)
	v_mul_f32_e32 v65, v129, v65
	v_mul_f32_e32 v72, v128, v72
	v_cvt_pk_bf16_f32 v65, v72, v65
	ds_read_b64 v[128:129], v126 offset:48
	v_lshlrev_b32_e32 v72, 16, v66
	v_and_b32_e32 v66, 0xffff0000, v66
	s_waitcnt lgkmcnt(0)
	v_mul_f32_e32 v66, v129, v66
	v_mul_f32_e32 v72, v128, v72
	v_cvt_pk_bf16_f32 v66, v72, v66
	ds_read_b64 v[128:129], v126 offset:56
	v_lshlrev_b32_e32 v72, 16, v67
	v_and_b32_e32 v67, 0xffff0000, v67
	s_waitcnt lgkmcnt(0)
	v_mul_f32_e32 v67, v129, v67
	v_mul_f32_e32 v72, v128, v72
	v_cvt_pk_bf16_f32 v67, v72, v67
	global_store_dwordx4 v[88:89], v[68:71], off
	global_store_dwordx4 v[88:89], v[64:67], off offset:16
	s_cbranch_scc0 .LBB0_459
.LBB0_454:
	global_load_dwordx4 v[68:71], v[82:83], off offset:48
	global_load_dwordx4 v[64:67], v[84:85], off offset:48
	s_waitcnt vmcnt(2)
	s_lshl_b32 s4, s3, 6
	v_add_u32_e32 v128, s4, v93
	v_cmp_lt_u32_e64 s[0:1], 2, v128
	s_nop 0
	v_lshlrev_b32_e32 v88, 16, v36
	v_and_b32_e32 v89, 0xffff0000, v36
	v_cndmask_b32_e64 v72, 0, 1.0, s[0:1]
	v_cmp_lt_u32_e64 s[0:1], 1, v128
	s_nop 0
	v_lshlrev_b32_e32 v186, 16, v44
	v_and_b32_e32 v187, 0xffff0000, v44
	v_cndmask_b32_e64 v234, 0, 1.0, s[0:1]
	v_cmp_eq_u32_e64 s[0:1], 0, v128
	v_lshlrev_b32_e32 v212, 16, v37
	v_and_b32_e32 v213, 0xffff0000, v37
	v_lshlrev_b32_e32 v220, 16, v38
	v_and_b32_e32 v221, 0xffff0000, v38
	v_lshlrev_b32_e32 v228, 16, v39
	v_and_b32_e32 v229, 0xffff0000, v39
	v_cndmask_b32_e64 v236, 1.0, 0, s[0:1]
	s_nop 0
	v_lshlrev_b32_e32 v208, 16, v52
	v_and_b32_e32 v209, 0xffff0000, v52
	v_lshlrev_b32_e32 v214, 16, v45
	v_and_b32_e32 v215, 0xffff0000, v45
	v_lshlrev_b32_e32 v222, 16, v46
	v_and_b32_e32 v223, 0xffff0000, v46
	v_lshlrev_b32_e32 v230, 16, v47
	v_and_b32_e32 v231, 0xffff0000, v47
	s_nop 0
	v_lshlrev_b32_e32 v210, 16, v60
	v_and_b32_e32 v211, 0xffff0000, v60
	v_lshlrev_b32_e32 v216, 16, v53
	v_and_b32_e32 v217, 0xffff0000, v53
	v_lshlrev_b32_e32 v224, 16, v54
	v_and_b32_e32 v225, 0xffff0000, v54
	v_lshlrev_b32_e32 v232, 16, v55
	v_and_b32_e32 v233, 0xffff0000, v55
	v_lshlrev_b32_e32 v218, 16, v61
	v_and_b32_e32 v219, 0xffff0000, v61
	v_lshlrev_b32_e32 v226, 16, v62
	v_and_b32_e32 v227, 0xffff0000, v62
	s_cmpk_eq_i32 s3, 0x7f
	s_nop 0
	v_pk_mul_f32 v[130:131], v[72:73], v[130:131] op_sel_hi:[0,1]
	s_nop 0
	v_pk_mul_f32 v[134:135], v[234:235], v[134:135] op_sel_hi:[0,1]
	v_pk_mul_f32 v[132:133], v[72:73], v[132:133] op_sel_hi:[0,1]
	s_nop 0
	v_pk_mul_f32 v[142:143], v[72:73], v[142:143] op_sel_hi:[0,1]
	v_pk_mul_f32 v[144:145], v[72:73], v[144:145] op_sel_hi:[0,1]
	v_pk_mul_f32 v[138:139], v[236:237], v[138:139] op_sel_hi:[0,1]
	s_nop 0
	v_pk_fma_f32 v[88:89], v[130:131], v[88:89], v[154:155]
	v_pk_mul_f32 v[136:137], v[234:235], v[136:137] op_sel_hi:[0,1]
	v_pk_mul_f32 v[146:147], v[234:235], v[146:147] op_sel_hi:[0,1]
	v_pk_mul_f32 v[148:149], v[234:235], v[148:149] op_sel_hi:[0,1]
	v_pk_fma_f32 v[130:131], v[132:133], v[212:213], v[156:157]
	s_nop 0
	v_pk_fma_f32 v[132:133], v[142:143], v[220:221], v[158:159]
	v_pk_fma_f32 v[142:143], v[144:145], v[228:229], v[160:161]
	v_pk_fma_f32 v[88:89], v[134:135], v[186:187], v[88:89]
; __device__ __forceinline__ unsigned cvt_pk_bf16(float lo, float hi) { unsigned r; asm volatile("v_cvt_pk_bf16_f32 %0, %1, %2" : "=v"(r) : "v"(lo), "v"(hi)); return r; }
; #define RG_LOAD(T0) do { _Pragma("unroll") for (int k = 0; k < 4; ++k) { int tk = (T0) + tt - 3 + k; tk = tk < 0 ? 0 : tk; const bf16_t* xp = P.XR + (rowb + tk) * 2048 + cg0; \
;             xr[k][0] = *(const u32x4*)xp; xr[k][1] = *(const u32x4*)(xp + 8); } } while (0)
; __device__ __forceinline__ void rglru_item(const Ptrs& P, unsigned char* lds, int b, int n, int tid) {
;     ...
;             for (int k = 0; k < 4; ++k) { const float m = (t0 + tt - 3 + k) >= 0 ? 1.f : 0.f;
;                 float cwk[16];
; #pragma unroll
;                 for (int e = 0; e < 16; e += 4) { const f32x4 c = *(const f32x4*)(P.conv_w + k * 2048 + cg0 + e); cwk[e] = c[0]; cwk[e + 1] = c[1]; cwk[e + 2] = c[2]; cwk[e + 3] = c[3]; }
;                 const u32x4 xa = xr[k][0], xb2 = xr[k][1];
;                 const float xv[16] = {bflo(xa.x), bfhi(xa.x), bflo(xa.y), bfhi(xa.y), bflo(xa.z), bfhi(xa.z), bflo(xa.w), bfhi(xa.w),
;                                       bflo(xb2.x), bfhi(xb2.x), bflo(xb2.y), bfhi(xb2.y), bflo(xb2.z), bfhi(xb2.z), bflo(xb2.w), bfhi(xb2.w)};
; #pragma unroll
;                 for (int e = 0; e < 16; ++e) xc[e] += (cwk[e] * m) * xv[e]; }
; #pragma unroll
;             for (int e = 0; e < 16; e += 4) *(f32x4*)(XCf + tt * 128 + c0 + e) = (f32x4){xc[e], xc[e + 1], xc[e + 2], xc[e + 3]};
;             u32x4 w0, w1; w0.x = cvt_pk_bf16(xc[0], xc[1]); w0.y = cvt_pk_bf16(xc[2], xc[3]); w0.z = cvt_pk_bf16(xc[4], xc[5]); w0.w = cvt_pk_bf16(xc[6], xc[7]);
;             w1.x = cvt_pk_bf16(xc[8], xc[9]); w1.y = cvt_pk_bf16(xc[10], xc[11]); w1.z = cvt_pk_bf16(xc[12], xc[13]); w1.w = cvt_pk_bf16(xc[14], xc[15]);
;             *(u32x4*)(XCb + tt * 136 + c0) = w0; *(u32x4*)(XCb + tt * 136 + c0 + 8) = w1;
;             { const bf16_t* gp_ = P.RG + (rowb + t0 + tt) * 2048 + cg0; gc0 = *(const u32x4*)gp_; gc1 = *(const u32x4*)(gp_ + 8); }
;             if (chunk + 1 < T / 64) RG_LOAD(t0 + 64);
	v_pk_mul_f32 v[140:141], v[236:237], v[140:141] op_sel_hi:[0,1]
	v_pk_mul_f32 v[150:151], v[236:237], v[150:151] op_sel_hi:[0,1]
	v_pk_mul_f32 v[152:153], v[236:237], v[152:153] op_sel_hi:[0,1]
	v_pk_fma_f32 v[130:131], v[136:137], v[214:215], v[130:131]
	v_pk_fma_f32 v[132:133], v[146:147], v[222:223], v[132:133]
	v_pk_fma_f32 v[134:135], v[148:149], v[230:231], v[142:143]
	v_pk_fma_f32 v[88:89], v[138:139], v[208:209], v[88:89]
	v_pk_fma_f32 v[136:137], v[140:141], v[216:217], v[130:131]
	v_pk_fma_f32 v[138:139], v[150:151], v[224:225], v[132:133]
	v_pk_fma_f32 v[140:141], v[152:153], v[232:233], v[134:135]
	s_nop 0
	v_pk_fma_f32 v[130:131], v[162:163], v[210:211], v[88:89]
	v_lshlrev_b32_e32 v88, 16, v63
	v_and_b32_e32 v89, 0xffff0000, v63
	v_pk_fma_f32 v[132:133], v[164:165], v[218:219], v[136:137]
	s_nop 0
	v_pk_fma_f32 v[134:135], v[166:167], v[226:227], v[138:139]
	v_pk_fma_f32 v[136:137], v[168:169], v[88:89], v[140:141]
	v_lshlrev_b32_e32 v88, 16, v32
	v_and_b32_e32 v89, 0xffff0000, v32
	s_nop 0
	v_pk_mul_f32 v[138:139], v[72:73], v[170:171] op_sel_hi:[0,1]
	s_nop 0
	v_pk_fma_f32 v[88:89], v[138:139], v[88:89], v[174:175]
	v_lshlrev_b32_e32 v138, 16, v40
	v_and_b32_e32 v139, 0xffff0000, v40
	s_nop 0
	v_pk_mul_f32 v[140:141], v[234:235], v[190:191] op_sel_hi:[0,1]
	v_pk_fma_f32 v[88:89], v[140:141], v[138:139], v[88:89]
	v_lshlrev_b32_e32 v138, 16, v48
	v_and_b32_e32 v139, 0xffff0000, v48
	s_nop 0
	v_pk_mul_f32 v[140:141], v[236:237], v[198:199] op_sel_hi:[0,1]
	v_pk_fma_f32 v[88:89], v[140:141], v[138:139], v[88:89]
	v_lshlrev_b32_e32 v138, 16, v56
	v_and_b32_e32 v139, 0xffff0000, v56
	s_nop 0
	v_pk_fma_f32 v[138:139], v[202:203], v[138:139], v[88:89]
	v_lshlrev_b32_e32 v88, 16, v33
	v_and_b32_e32 v89, 0xffff0000, v33
	v_pk_mul_f32 v[140:141], v[72:73], v[172:173] op_sel_hi:[0,1]
	v_pk_fma_f32 v[88:89], v[140:141], v[88:89], v[176:177]
	v_lshlrev_b32_e32 v140, 16, v41
	v_and_b32_e32 v141, 0xffff0000, v41
	v_pk_mul_f32 v[142:143], v[234:235], v[192:193] op_sel_hi:[0,1]
	v_pk_fma_f32 v[88:89], v[142:143], v[140:141], v[88:89]
	v_lshlrev_b32_e32 v140, 16, v49
	v_and_b32_e32 v141, 0xffff0000, v49
	v_pk_mul_f32 v[142:143], v[236:237], v[200:201] op_sel_hi:[0,1]
	v_pk_fma_f32 v[88:89], v[142:143], v[140:141], v[88:89]
	v_lshlrev_b32_e32 v140, 16, v57
	v_and_b32_e32 v141, 0xffff0000, v57
	v_pk_fma_f32 v[140:141], v[204:205], v[140:141], v[88:89]
	v_lshlrev_b32_e32 v88, 16, v34
	v_and_b32_e32 v89, 0xffff0000, v34
	v_pk_mul_f32 v[142:143], v[72:73], v[182:183] op_sel_hi:[0,1]
	v_pk_fma_f32 v[88:89], v[142:143], v[88:89], v[178:179]
	v_lshlrev_b32_e32 v142, 16, v42
	v_and_b32_e32 v143, 0xffff0000, v42
	v_pk_mul_f32 v[144:145], v[234:235], v[194:195] op_sel_hi:[0,1]
	v_pk_fma_f32 v[88:89], v[144:145], v[142:143], v[88:89]
	v_lshlrev_b32_e32 v142, 16, v50
	v_and_b32_e32 v143, 0xffff0000, v50
	s_waitcnt vmcnt(0)
	v_pk_mul_f32 v[68:69], v[236:237], v[68:69] op_sel_hi:[0,1]
	v_pk_fma_f32 v[68:69], v[68:69], v[142:143], v[88:89]
	v_lshlrev_b32_e32 v88, 16, v58
	v_and_b32_e32 v89, 0xffff0000, v58
	v_pk_fma_f32 v[64:65], v[64:65], v[88:89], v[68:69]
	v_lshlrev_b32_e32 v68, 16, v35
	v_and_b32_e32 v69, 0xffff0000, v35
	v_pk_mul_f32 v[88:89], v[72:73], v[184:185] op_sel_hi:[0,1]
	v_pk_fma_f32 v[68:69], v[88:89], v[68:69], v[180:181]
	v_lshlrev_b32_e32 v88, 16, v43
	v_and_b32_e32 v89, 0xffff0000, v43
	v_pk_mul_f32 v[142:143], v[234:235], v[196:197] op_sel_hi:[0,1]
	v_pk_fma_f32 v[68:69], v[142:143], v[88:89], v[68:69]
	v_lshlrev_b32_e32 v88, 16, v51
	v_and_b32_e32 v89, 0xffff0000, v51
	v_pk_mul_f32 v[70:71], v[236:237], v[70:71] op_sel_hi:[0,1]
	v_pk_fma_f32 v[68:69], v[70:71], v[88:89], v[68:69]
	v_lshlrev_b32_e32 v70, 16, v59
	v_and_b32_e32 v71, 0xffff0000, v59
	v_add_u32_e32 v72, s4, v94
	v_pk_fma_f32 v[66:67], v[66:67], v[70:71], v[68:69]
	ds_write_b128 v95, v[130:133] offset:17408
	ds_write_b128 v95, v[134:137] offset:17424
	ds_write_b128 v95, v[138:141] offset:17440
	ds_write_b128 v95, v[64:67] offset:17456
	v_cvt_pk_bf16_f32 v130, v130, v131
	v_cvt_pk_bf16_f32 v131, v132, v133
	v_cvt_pk_bf16_f32 v132, v134, v135
	v_cvt_pk_bf16_f32 v133, v136, v137
	v_cvt_pk_bf16_f32 v134, v138, v139
	v_cvt_pk_bf16_f32 v135, v140, v141
	v_cvt_pk_bf16_f32 v136, v64, v65
	v_lshlrev_b64 v[64:65], 12, v[72:73]
	v_lshl_add_u64 v[88:89], v[86:87], 0, v[64:65]
	v_cvt_pk_bf16_f32 v137, v66, v67
	global_load_dwordx4 v[64:67], v[88:89], off offset:16
	global_load_dwordx4 v[68:71], v[88:89], off
	ds_write_b128 v123, v[130:133]
	ds_write_b128 v123, v[134:137] offset:16
	s_cbranch_scc1 .LBB0_456
	v_add_u32_e32 v56, 61, v128
	v_add_u32_e32 v72, s6, v56
	v_lshlrev_b64 v[32:33], 12, v[72:73]
	v_add_u32_e32 v72, s7, v56
	v_lshlrev_b64 v[40:41], 12, v[72:73]
	v_add_u32_e32 v72, s8, v56
	v_lshlrev_b64 v[48:49], 12, v[72:73]
	v_add_u32_e32 v72, s9, v56
	v_lshlrev_b64 v[56:57], 12, v[72:73]
	v_lshl_add_u64 v[36:37], v[74:75], 0, v[32:33]
	v_lshl_add_u64 v[44:45], v[74:75], 0, v[40:41]
	v_lshl_add_u64 v[52:53], v[74:75], 0, v[48:49]
	v_lshl_add_u64 v[60:61], v[74:75], 0, v[56:57]
	global_load_dwordx4 v[32:35], v[36:37], off offset:16
	s_nop 0
	global_load_dwordx4 v[36:39], v[36:37], off
	s_nop 0
	global_load_dwordx4 v[40:43], v[44:45], off offset:16
	s_nop 0
	global_load_dwordx4 v[44:47], v[44:45], off
	s_nop 0
	global_load_dwordx4 v[48:51], v[52:53], off offset:16
	s_nop 0
	global_load_dwordx4 v[52:55], v[52:53], off
	s_nop 0
	global_load_dwordx4 v[56:59], v[60:61], off offset:16
	s_nop 0
	global_load_dwordx4 v[60:63], v[60:61], off

; __device__ __forceinline__ void rglru_item(const Ptrs& P, unsigned char* lds, int b, int n, int tid) {
;     ...
;         if (tid < 128) {
; #pragma unroll 1
;             for (int t16 = 0; t16 < 64; t16 += 16) { float av[16], bv[16];
; #pragma unroll
;                 for (int e = 0; e < 16; ++e) { av[e] = LA[(t16 + e) * 128 + tid]; bv[e] = LB[(t16 + e) * 128 + tid]; }
; #pragma unroll
;                 for (int e = 0; e < 16; ++e) { h = av[e] * h + bv[e]; LB[(t16 + e) * 128 + tid] = h; } }
;         }
;     ...
;     __syncthreads();
; __global__ void __launch_bounds__(512, 2) mega_fwd(Args args) {
;     ...
;         if (tid < 64) ((volatile unsigned*)(lds + 147456))[tid] = 0u;
.LBB0_458:
	ds_read2st64_b32 v[128:129], v72 offset1:2
	ds_read2st64_b32 v[130:131], v72 offset0:128 offset1:130
	ds_read2st64_b32 v[132:133], v72 offset0:4 offset1:6
	ds_read2st64_b32 v[134:135], v72 offset0:132 offset1:134
	ds_read2st64_b32 v[136:137], v72 offset0:8 offset1:10
	ds_read2st64_b32 v[138:139], v72 offset0:136 offset1:138
	ds_read2st64_b32 v[140:141], v72 offset0:12 offset1:14
	ds_read2st64_b32 v[142:143], v72 offset0:140 offset1:142
	ds_read2st64_b32 v[144:145], v72 offset0:16 offset1:18
	ds_read2st64_b32 v[146:147], v72 offset0:144 offset1:146
	ds_read2st64_b32 v[148:149], v72 offset0:20 offset1:22
	ds_read2st64_b32 v[150:151], v72 offset0:148 offset1:150
	ds_read2st64_b32 v[152:153], v72 offset0:24 offset1:26
	ds_read2st64_b32 v[154:155], v72 offset0:152 offset1:154
	ds_read2st64_b32 v[156:157], v72 offset0:28 offset1:30
	ds_read2st64_b32 v[158:159], v72 offset0:156 offset1:158
	s_waitcnt lgkmcnt(14)
	v_fma_f32 v127, v127, v128, v130
	v_fmac_f32_e32 v131, v127, v129
	ds_write2st64_b32 v72, v127, v131 offset0:128 offset1:130
	s_waitcnt lgkmcnt(13)
	v_fma_f32 v127, v131, v132, v134
	v_fmac_f32_e32 v135, v127, v133
	ds_write2st64_b32 v72, v127, v135 offset0:132 offset1:134
	s_waitcnt lgkmcnt(12)
	v_fma_f32 v127, v135, v136, v138
	v_fmac_f32_e32 v139, v127, v137
	ds_write2st64_b32 v72, v127, v139 offset0:136 offset1:138
	s_waitcnt lgkmcnt(11)
	v_fma_f32 v127, v139, v140, v142
	v_fmac_f32_e32 v143, v127, v141
	ds_write2st64_b32 v72, v127, v143 offset0:140 offset1:142
	s_waitcnt lgkmcnt(10)
	v_fma_f32 v127, v143, v144, v146
	v_fmac_f32_e32 v147, v127, v145
	ds_write2st64_b32 v72, v127, v147 offset0:144 offset1:146
	s_waitcnt lgkmcnt(9)
	v_fma_f32 v127, v147, v148, v150
	v_fmac_f32_e32 v151, v127, v149
	ds_write2st64_b32 v72, v127, v151 offset0:148 offset1:150
	s_waitcnt lgkmcnt(8)
	v_fma_f32 v127, v151, v152, v154
	v_fmac_f32_e32 v155, v127, v153
	ds_write2st64_b32 v72, v127, v155 offset0:152 offset1:154
	s_waitcnt lgkmcnt(7)
	v_fma_f32 v128, v155, v156, v158
	v_mov_b32_e32 v127, v159
	v_fmac_f32_e32 v127, v128, v157
	s_add_i32 s4, s4, 16
	ds_write2st64_b32 v72, v128, v127 offset0:156 offset1:158
	s_cmp_lt_u32 s4, 48
	v_add_u32_e32 v72, 0x2000, v72
	s_cbranch_scc1 .LBB0_458
	s_branch .LBB0_453
.LBB0_459:
	s_waitcnt vmcnt(0)
	s_barrier
.LBB0_460:
	v_cmp_gt_u32_e32 vcc, 64, v188
	s_and_saveexec_b64 s[0:1], vcc
	s_cbranch_execz .LBB0_462
	s_mov_b64 s[4:5], src_shared_base
	s_add_i32 s3, 0, 0x24000
	v_lshl_add_u32 v0, v188, 2, s3
	v_mov_b32_e32 v1, s5
	v_mov_b32_e32 v2, 0
	ds_write_b32 v0, v2
	s_waitcnt vmcnt(0) lgkmcnt(0)
